# attention: the end-of-step barrier (B6) removed - with the V-piece DMA issued after the PV barrier it only ordered the merge reads against the next step's partial writes, which the next step's barrier
# baseline (speedup 1.0000x reference)
; #define SCHED_FENCE() __builtin_amdgcn_sched_barrier(0)
; #define ATT_V_PIECE(h_, row_, dg_) do { const int dh = (dg_) * 8 + lr; \
;         __builtin_amdgcn_global_load_lds((const __attribute__((address_space(1))) unsigned*)(VTa + (size_t)((h_) * 64 + dh) * T + (size_t)(row_) * 64 + 8 * (lc ^ att_fv(dh))), (LAS unsigned*)(VL + ((row_) & 7) * 8192 + (dg_) * 1024), 16, 0, 0); } while (0)
; #define ATT_BAR() do { asm volatile("s_waitcnt lgkmcnt(0)" ::: "memory"); __builtin_amdgcn_s_barrier(); asm volatile("" ::: "memory"); } while (0)
; __device__ __forceinline__ void attn_phase(const bf16_t* Q, const bf16_t* Kb, const bf16_t* VTa, const float* rpb, bf16_t* Y, LAS unsigned char* lds, int bx, int G, int tid, int wave, int lane) {
;     ...
;             ATT_BAR();
;             SCHED_FENCE();
;             if (newrow) ATT_V_PIECE(h, rs + 8, wave);
;             SCHED_FENCE();
;         }
;         asm volatile("s_waitcnt vmcnt(0) lgkmcnt(0)" ::: "memory");
;         __builtin_amdgcn_s_barrier();
.LBB0_447:
	s_waitcnt lgkmcnt(0)
	s_waitcnt lgkmcnt(0)
	s_add_i32 s92, s92, s96
	s_cmpk_gt_i32 s92, 0xff
	s_barrier
	s_cbranch_scc1 .LBB0_469

; #define SCHED_FENCE() __builtin_amdgcn_sched_barrier(0)
; #define ATT_V_PIECE(h_, row_, dg_) do { const int dh = (dg_) * 8 + lr; \
;         __builtin_amdgcn_global_load_lds((const __attribute__((address_space(1))) unsigned*)(VTa + (size_t)((h_) * 64 + dh) * T + (size_t)(row_) * 64 + 8 * (lc ^ att_fv(dh))), (LAS unsigned*)(VL + ((row_) & 7) * 8192 + (dg_) * 1024), 16, 0, 0); } while (0)
; #define ATT_BAR() do { asm volatile("s_waitcnt lgkmcnt(0)" ::: "memory"); __builtin_amdgcn_s_barrier(); asm volatile("" ::: "memory"); } while (0)
; __device__ __forceinline__ void attn_phase(const bf16_t* Q, const bf16_t* Kb, const bf16_t* VTa, const float* rpb, bf16_t* Y, LAS unsigned char* lds, int bx, int G, int tid, int wave, int lane) {
;     ...
;             ATT_BAR();
;             SCHED_FENCE();
;             if (newrow) ATT_V_PIECE(h, rs + 8, wave);
;             SCHED_FENCE();
;         }
.LBB0_461:
.LBB0_463:
	s_add_i32 s30, s30, -1
	s_add_i32 s94, s94, 1
	s_cmp_eq_u32 s30, 0
	s_cbranch_scc1 .LBB0_465
	v_mov_b32_e32 v98, v30
	s_branch .LBB0_451
